# in-proj GEMM tile start: both vmcnt(0) drains removed (the first K-stage wait covers the older stores in order)
# speedup vs baseline: 1.0066x; 1.0066x over previous
.LBB0_219:
	s_lshr_b32 s2, s4, 2
	s_and_b32 s3, s4, 3
	s_lshl_b32 s3, s3, 3
	s_mov_b32 s6, 0x1001000a
	s_cmp_eq_u32 s2, 1
	s_cselect_b32 s6, 0x171b0611, s6
	s_cmp_eq_u32 s2, 2
	s_cselect_b32 s6, 0xe1c1d08, s6
	s_cmp_eq_u32 s2, 3
	s_cselect_b32 s6, 0x14090203, s6
	s_cmp_eq_u32 s2, 4
	s_cselect_b32 s6, 0x40f0512, s6
	s_cmp_eq_u32 s2, 5
	s_cselect_b32 s6, 0xc160b0d, s6
	s_cmp_eq_u32 s2, 6
	s_cselect_b32 s6, 0x191a1813, s6
	s_cmp_eq_u32 s2, 7
	s_cselect_b32 s6, 0x1507, s6
	s_lshr_b32 s6, s6, s3
	s_and_b32 s4, s6, 0xff
	s_lshl_b32 s5, s5, 8
	v_add_u32_e32 v2, s5, v219
	v_ashrrev_i32_e32 v3, 31, v2
	v_lshlrev_b64 v[4:5], 11, v[2:3]
	v_and_b32_e32 v6, 0xfffe7000, v4
	v_mov_b32_e32 v7, v5
	v_lshlrev_b32_e32 v0, 6, v2
	s_lshl_b32 s6, s4, 7
	v_lshl_add_u64 v[6:7], s[44:45], 0, v[6:7]
	v_and_b32_e32 v0, 64, v0
	v_lshl_add_u64 v[2:3], v[6:7], 0, v[0:1]
	v_add_u32_e32 v6, s6, v220
	v_ashrrev_i32_e32 v7, 31, v6
	v_lshlrev_b64 v[8:9], 11, v[6:7]
	v_and_b32_e32 v10, 0xffff7000, v8
	v_mov_b32_e32 v11, v9
	v_lshlrev_b32_e32 v0, 6, v6
	v_lshl_add_u64 v[10:11], s[42:43], 0, v[10:11]
	v_and_b32_e32 v0, 64, v0
	v_mov_b32_e32 v139, v1
	v_lshl_add_u64 v[6:7], v[10:11], 0, v[0:1]
	v_readfirstlane_b32 s2, v221
	v_add_u32_e32 v0, 0x400, v221
	v_lshl_add_u64 v[2:3], v[2:3], 0, v[138:139]
	s_nop 0
	s_mov_b32 m0, s2
	s_mov_b64 s[8:9], 0x8000
	v_readfirstlane_b32 s2, v0
	global_load_lds_dwordx4 v[2:3], off
	v_lshl_add_u64 v[10:11], v[2:3], 0, s[8:9]
	s_mov_b32 m0, s2
	s_mov_b64 s[2:3], 0x10000
	v_add_u32_e32 v0, 0x800, v221
	global_load_lds_dwordx4 v[10:11], off
	v_lshl_add_u64 v[10:11], v[2:3], 0, s[2:3]
	v_readfirstlane_b32 s2, v0
	s_mov_b32 m0, s2
	s_mov_b64 s[2:3], 0x18000
	v_add_u32_e32 v0, 0xc00, v221
	global_load_lds_dwordx4 v[10:11], off
	v_lshl_add_u64 v[10:11], v[2:3], 0, s[2:3]
	v_readfirstlane_b32 s2, v0
	v_add_u32_e32 v0, 0x4000, v130
	s_mov_b32 m0, s2
	v_readfirstlane_b32 s2, v0
	v_add_u32_e32 v0, 0x4400, v130
	v_lshl_add_u64 v[6:7], v[6:7], 0, v[138:139]
	global_load_lds_dwordx4 v[10:11], off
	s_mov_b32 m0, s2
	v_readfirstlane_b32 s2, v0
	v_add_u32_e32 v0, 0x6000, v221
	global_load_lds_dwordx4 v[6:7], off
	v_lshl_add_u64 v[10:11], v[6:7], 0, s[8:9]
	s_mov_b32 m0, s2
	s_mov_b64 s[8:9], 0x80
	v_readfirstlane_b32 s2, v0
	v_add_u32_e32 v0, 0x6400, v221
	global_load_lds_dwordx4 v[10:11], off
	v_lshl_add_u64 v[10:11], v[2:3], 0, s[8:9]
	s_mov_b32 m0, s2
	s_mov_b64 s[30:31], 0x8080
	v_readfirstlane_b32 s2, v0
	global_load_lds_dwordx4 v[10:11], off
	v_lshl_add_u64 v[10:11], v[2:3], 0, s[30:31]
	s_mov_b32 m0, s2
	s_mov_b64 s[2:3], 0x10080
	v_add_u32_e32 v0, 0x6800, v221
	global_load_lds_dwordx4 v[10:11], off
	v_lshl_add_u64 v[10:11], v[2:3], 0, s[2:3]
	v_readfirstlane_b32 s2, v0
	s_mov_b32 m0, s2
	s_mov_b64 s[2:3], 0x18080
	v_add_u32_e32 v0, 0x6c00, v221
	v_lshl_add_u64 v[2:3], v[2:3], 0, s[2:3]
	v_readfirstlane_b32 s2, v0
	v_add_u32_e32 v0, 0xa000, v130
	global_load_lds_dwordx4 v[10:11], off
	s_mov_b32 m0, s2
	v_readfirstlane_b32 s2, v0
	v_add_u32_e32 v0, 0xa400, v130
	global_load_lds_dwordx4 v[2:3], off
	v_lshl_add_u64 v[2:3], v[6:7], 0, s[8:9]
	s_mov_b32 m0, s2
	v_readfirstlane_b32 s2, v0
	global_load_lds_dwordx4 v[2:3], off
	v_lshl_add_u64 v[2:3], v[6:7], 0, s[30:31]
	s_mov_b32 m0, s2
	v_and_b32_e32 v8, 0xfffff000, v8
	global_load_lds_dwordx4 v[2:3], off
	v_and_b32_e32 v4, 0xfffff000, v4
	v_mov_b32_e32 v2, 0
	v_lshl_add_u64 v[142:143], v[134:135], 0, v[8:9]
	v_lshl_add_u64 v[144:145], v[136:137], 0, v[4:5]
	s_mov_b32 s7, 0
	s_mov_b64 s[2:3], 0
	v_mov_b32_e32 v3, v2
	v_mov_b32_e32 v4, v2
	v_mov_b32_e32 v5, v2
	v_mov_b32_e32 v6, v2
	v_mov_b32_e32 v7, v2
	v_mov_b32_e32 v8, v2
	v_mov_b32_e32 v9, v2
	v_mov_b32_e32 v10, v2
	v_mov_b32_e32 v11, v2
	v_mov_b32_e32 v12, v2
	v_mov_b32_e32 v13, v2
	v_mov_b32_e32 v14, v2
	v_mov_b32_e32 v15, v2
	v_mov_b32_e32 v16, v2
	v_mov_b32_e32 v17, v2
	v_mov_b32_e32 v18, v2
	v_mov_b32_e32 v19, v2
	v_mov_b32_e32 v20, v2
	v_mov_b32_e32 v21, v2
	v_mov_b32_e32 v22, v2
	v_mov_b32_e32 v23, v2
	v_mov_b32_e32 v24, v2
	v_mov_b32_e32 v25, v2
	v_mov_b32_e32 v26, v2
	v_mov_b32_e32 v27, v2
	v_mov_b32_e32 v28, v2
	v_mov_b32_e32 v29, v2
	v_mov_b32_e32 v30, v2
	v_mov_b32_e32 v31, v2
	v_mov_b32_e32 v32, v2
	v_mov_b32_e32 v33, v2
	v_mov_b32_e32 v34, v2
	v_mov_b32_e32 v35, v2
	v_mov_b32_e32 v36, v2
	v_mov_b32_e32 v37, v2
	v_mov_b32_e32 v38, v2
	v_mov_b32_e32 v39, v2
	v_mov_b32_e32 v40, v2
	v_mov_b32_e32 v41, v2
	v_mov_b32_e32 v42, v2
	v_mov_b32_e32 v43, v2
	v_mov_b32_e32 v44, v2
	v_mov_b32_e32 v45, v2
	v_mov_b32_e32 v46, v2
	v_mov_b32_e32 v47, v2
	v_mov_b32_e32 v48, v2
	v_mov_b32_e32 v49, v2
	s_nop 0
	v_mov_b32_e32 v50, v2
	v_mov_b32_e32 v51, v2
	v_mov_b32_e32 v52, v2
	v_mov_b32_e32 v53, v2
	v_mov_b32_e32 v54, v2
	v_mov_b32_e32 v55, v2
	v_mov_b32_e32 v56, v2
	v_mov_b32_e32 v57, v2
	v_mov_b32_e32 v58, v2
	v_mov_b32_e32 v59, v2
	v_mov_b32_e32 v60, v2
	v_mov_b32_e32 v61, v2
	v_mov_b32_e32 v62, v2
	v_mov_b32_e32 v63, v2
	v_mov_b32_e32 v64, v2
	v_mov_b32_e32 v65, v2
	v_mov_b32_e32 v66, v2
	v_mov_b32_e32 v67, v2
	v_mov_b32_e32 v68, v2
	v_mov_b32_e32 v69, v2
	v_mov_b32_e32 v70, v2
	v_mov_b32_e32 v71, v2
	v_mov_b32_e32 v72, v2
	v_mov_b32_e32 v73, v2
	v_mov_b32_e32 v74, v2
	v_mov_b32_e32 v75, v2
	v_mov_b32_e32 v76, v2
	v_mov_b32_e32 v77, v2
	v_mov_b32_e32 v78, v2
	v_mov_b32_e32 v79, v2
	v_mov_b32_e32 v80, v2
	v_mov_b32_e32 v81, v2
	v_mov_b32_e32 v82, v2
	v_mov_b32_e32 v83, v2
	v_mov_b32_e32 v84, v2
	v_mov_b32_e32 v85, v2
	v_mov_b32_e32 v86, v2
	v_mov_b32_e32 v87, v2
	v_mov_b32_e32 v88, v2
	v_mov_b32_e32 v89, v2
	v_mov_b32_e32 v90, v2
	v_mov_b32_e32 v91, v2
	v_mov_b32_e32 v92, v2
	v_mov_b32_e32 v93, v2
	v_mov_b32_e32 v94, v2
	v_mov_b32_e32 v95, v2
	v_mov_b32_e32 v96, v2
	v_mov_b32_e32 v97, v2
	v_mov_b32_e32 v98, v2
	v_mov_b32_e32 v99, v2
	v_mov_b32_e32 v100, v2
	v_mov_b32_e32 v101, v2
	v_mov_b32_e32 v102, v2
	v_mov_b32_e32 v103, v2
	v_mov_b32_e32 v104, v2
	v_mov_b32_e32 v105, v2
	v_mov_b32_e32 v106, v2
	v_mov_b32_e32 v107, v2
	v_mov_b32_e32 v108, v2
	v_mov_b32_e32 v109, v2
	v_mov_b32_e32 v110, v2
	v_mov_b32_e32 v111, v2
	v_mov_b32_e32 v112, v2
	v_mov_b32_e32 v113, v2
	v_mov_b32_e32 v114, v2
	v_mov_b32_e32 v115, v2
	v_mov_b32_e32 v116, v2
	v_mov_b32_e32 v117, v2
	v_mov_b32_e32 v118, v2
	v_mov_b32_e32 v119, v2
	v_mov_b32_e32 v120, v2
	v_mov_b32_e32 v121, v2
	v_mov_b32_e32 v122, v2
	v_mov_b32_e32 v123, v2
	v_mov_b32_e32 v124, v2
	v_mov_b32_e32 v125, v2
	v_mov_b32_e32 v126, v2
	v_mov_b32_e32 v127, v2
	v_mov_b32_e32 v128, v2
	v_mov_b32_e32 v129, v2
